# proj_and_up_gemm_epilogue_stores_sc1_nt_P1_P6_P8_P14
# speedup vs baseline: 1.0161x; 1.0005x over previous
.LBB0_403:
	s_cmp_eq_u32 s63, -1
	v_lshl_add_u32 v146, s30, 8, v150
	s_cbranch_scc1 .LBB0_406
	v_lshl_or_b32 v148, s63, 8, v153
	v_ashrrev_i32_e32 v149, 31, v148
	v_mov_b64_e32 v[164:165], s[8:9]
	v_mad_i64_i32 v[158:159], s[0:1], v146, s58, v[164:165]
	v_lshlrev_b64 v[148:149], 1, v[148:149]
	v_lshl_add_u64 v[166:167], v[158:159], 0, v[148:149]
	v_cvt_pk_bf16_f32 v158, v84, v85
	v_cvt_pk_bf16_f32 v159, v86, v87
	v_cvt_pk_bf16_f32 v160, v80, v81
	v_cvt_pk_bf16_f32 v161, v82, v83
	global_store_dwordx4 v[166:167], v[158:161], off sc1 nt
	s_nop 1
	v_cvt_pk_bf16_f32 v124, v124, v125
	v_cvt_pk_bf16_f32 v125, v126, v127
	v_cvt_pk_bf16_f32 v126, v120, v121
	v_lshl_add_u64 v[120:121], v[166:167], 0, s[16:17]
	v_cvt_pk_bf16_f32 v127, v122, v123
	global_store_dwordx4 v[120:121], v[124:127], off sc1 nt
	s_nop 1
	v_or_b32_e32 v120, 16, v146
	v_mad_i64_i32 v[120:121], s[0:1], v120, s58, v[164:165]
	v_lshl_add_u64 v[124:125], v[120:121], 0, v[148:149]
	v_cvt_pk_bf16_f32 v120, v68, v69
	v_cvt_pk_bf16_f32 v121, v70, v71
	v_cvt_pk_bf16_f32 v122, v64, v65
	v_cvt_pk_bf16_f32 v123, v66, v67
	global_store_dwordx4 v[124:125], v[120:123], off sc1 nt
	s_nop 1
	v_cvt_pk_bf16_f32 v116, v116, v117
	v_cvt_pk_bf16_f32 v117, v118, v119
	v_cvt_pk_bf16_f32 v118, v112, v113
	v_lshl_add_u64 v[112:113], v[124:125], 0, s[16:17]
	v_cvt_pk_bf16_f32 v119, v114, v115
	global_store_dwordx4 v[112:113], v[116:119], off sc1 nt
	s_nop 1
	v_or_b32_e32 v112, 32, v146
	v_mad_i64_i32 v[112:113], s[0:1], v112, s58, v[164:165]
	v_lshl_add_u64 v[116:117], v[112:113], 0, v[148:149]
	v_cvt_pk_bf16_f32 v112, v52, v53
	v_cvt_pk_bf16_f32 v113, v54, v55
	v_cvt_pk_bf16_f32 v114, v48, v49
	v_cvt_pk_bf16_f32 v115, v50, v51
	global_store_dwordx4 v[116:117], v[112:115], off sc1 nt
	s_nop 1
	v_cvt_pk_bf16_f32 v108, v108, v109
	v_cvt_pk_bf16_f32 v109, v110, v111
	v_cvt_pk_bf16_f32 v110, v104, v105
	v_lshl_add_u64 v[104:105], v[116:117], 0, s[16:17]
	v_cvt_pk_bf16_f32 v111, v106, v107
	global_store_dwordx4 v[104:105], v[108:111], off sc1 nt
	s_nop 1
	v_or_b32_e32 v104, 48, v146
	v_mad_i64_i32 v[104:105], s[0:1], v104, s58, v[164:165]
	v_lshl_add_u64 v[108:109], v[104:105], 0, v[148:149]
	v_cvt_pk_bf16_f32 v104, v36, v37
	v_cvt_pk_bf16_f32 v105, v38, v39
	v_cvt_pk_bf16_f32 v106, v32, v33
	v_cvt_pk_bf16_f32 v107, v34, v35
	global_store_dwordx4 v[108:109], v[104:107], off sc1 nt
	s_nop 1
	v_cvt_pk_bf16_f32 v100, v100, v101
	v_cvt_pk_bf16_f32 v101, v102, v103
	v_cvt_pk_bf16_f32 v102, v96, v97
	v_lshl_add_u64 v[96:97], v[108:109], 0, s[16:17]
	v_cvt_pk_bf16_f32 v103, v98, v99
	global_store_dwordx4 v[96:97], v[100:103], off sc1 nt
	s_nop 1
	v_add_u32_e32 v96, 0x80, v146
	v_mad_i64_i32 v[96:97], s[0:1], v96, s58, v[164:165]
	v_lshl_add_u64 v[100:101], v[96:97], 0, v[148:149]
	v_cvt_pk_bf16_f32 v96, v28, v29
	v_cvt_pk_bf16_f32 v97, v30, v31
	v_cvt_pk_bf16_f32 v98, v24, v25
	v_cvt_pk_bf16_f32 v99, v26, v27
	global_store_dwordx4 v[100:101], v[96:99], off sc1 nt
	s_nop 1
	v_cvt_pk_bf16_f32 v92, v92, v93
	v_cvt_pk_bf16_f32 v93, v94, v95
	v_cvt_pk_bf16_f32 v94, v88, v89
	v_lshl_add_u64 v[88:89], v[100:101], 0, s[16:17]
	v_cvt_pk_bf16_f32 v95, v90, v91
	global_store_dwordx4 v[88:89], v[92:95], off sc1 nt
	s_nop 1
	v_add_u32_e32 v88, 0x90, v146
	v_mad_i64_i32 v[88:89], s[0:1], v88, s58, v[164:165]
	v_lshl_add_u64 v[92:93], v[88:89], 0, v[148:149]
	v_cvt_pk_bf16_f32 v88, v20, v21
	v_cvt_pk_bf16_f32 v89, v22, v23
	v_cvt_pk_bf16_f32 v90, v16, v17
	v_cvt_pk_bf16_f32 v91, v18, v19
	global_store_dwordx4 v[92:93], v[88:91], off sc1 nt
	s_nop 1
	v_cvt_pk_bf16_f32 v76, v76, v77
	v_cvt_pk_bf16_f32 v77, v78, v79
	v_cvt_pk_bf16_f32 v78, v72, v73
	v_lshl_add_u64 v[72:73], v[92:93], 0, s[16:17]
	v_cvt_pk_bf16_f32 v79, v74, v75
	global_store_dwordx4 v[72:73], v[76:79], off sc1 nt
	s_nop 1
	v_add_u32_e32 v72, 0xa0, v146
	v_mad_i64_i32 v[72:73], s[0:1], v72, s58, v[164:165]
	v_lshl_add_u64 v[76:77], v[72:73], 0, v[148:149]
	v_cvt_pk_bf16_f32 v72, v12, v13
	v_cvt_pk_bf16_f32 v73, v14, v15
	v_cvt_pk_bf16_f32 v74, v8, v9
	v_cvt_pk_bf16_f32 v75, v10, v11
	global_store_dwordx4 v[76:77], v[72:75], off sc1 nt
	s_nop 1
	v_cvt_pk_bf16_f32 v60, v60, v61
	v_cvt_pk_bf16_f32 v61, v62, v63
	v_cvt_pk_bf16_f32 v62, v56, v57
	v_lshl_add_u64 v[56:57], v[76:77], 0, s[16:17]
	v_cvt_pk_bf16_f32 v63, v58, v59
	global_store_dwordx4 v[56:57], v[60:63], off sc1 nt
	s_nop 1
	v_add_u32_e32 v56, 0xb0, v146
	v_mad_i64_i32 v[56:57], s[0:1], v56, s58, v[164:165]
	v_lshl_add_u64 v[60:61], v[56:57], 0, v[148:149]
	v_cvt_pk_bf16_f32 v56, v4, v5
	v_cvt_pk_bf16_f32 v57, v6, v7
	v_cvt_pk_bf16_f32 v58, v0, v1
	v_cvt_pk_bf16_f32 v59, v2, v3
	global_store_dwordx4 v[60:61], v[56:59], off sc1 nt
	s_nop 1
	v_cvt_pk_bf16_f32 v44, v44, v45
	v_cvt_pk_bf16_f32 v45, v46, v47
	v_cvt_pk_bf16_f32 v46, v40, v41
	v_cvt_pk_bf16_f32 v47, v42, v43
	v_lshl_add_u64 v[40:41], v[60:61], 0, s[16:17]
	global_store_dwordx4 v[40:41], v[44:47], off sc1 nt
	s_nop 1
	s_cbranch_execz .LBB0_407
	s_andn2_b64 vcc, exec, s[6:7]
	s_mov_b64 s[0:1], -1
	s_cbranch_vccnz .LBB0_396
	s_branch .LBB0_410

.LBB0_1199:
	v_lshl_add_u32 v147, s60, 10, v154
	ds_read_b32 v164, v147
	v_lshl_or_b32 v150, s61, 8, v155
	v_ashrrev_i32_e32 v151, 31, v150
	v_mov_b64_e32 v[148:149], s[8:9]
	v_mad_i64_i32 v[160:161], s[0:1], v146, s56, v[148:149]
	v_lshlrev_b64 v[150:151], 1, v[150:151]
	v_lshl_add_u64 v[166:167], v[160:161], 0, v[150:151]
	s_waitcnt lgkmcnt(0)
	v_pk_mul_f32 v[162:163], v[78:79], v[164:165] op_sel_hi:[1,0]
	v_pk_mul_f32 v[160:161], v[76:77], v[164:165] op_sel_hi:[1,0]
	v_pk_mul_f32 v[172:173], v[74:75], v[164:165] op_sel_hi:[1,0]
	v_pk_mul_f32 v[174:175], v[72:73], v[164:165] op_sel_hi:[1,0]
	v_cvt_pk_bf16_f32 v160, v160, v161
	v_cvt_pk_bf16_f32 v161, v162, v163
	v_cvt_pk_bf16_f32 v162, v174, v175
	v_cvt_pk_bf16_f32 v163, v172, v173
	global_store_dwordx4 v[166:167], v[160:163], off sc1 nt
	s_nop 1
	v_pk_mul_f32 v[126:127], v[126:127], v[164:165] op_sel_hi:[1,0]
	v_pk_mul_f32 v[124:125], v[124:125], v[164:165] op_sel_hi:[1,0]
	v_pk_mul_f32 v[160:161], v[122:123], v[164:165] op_sel_hi:[1,0]
	v_pk_mul_f32 v[122:123], v[120:121], v[164:165] op_sel_hi:[1,0]
	v_cvt_pk_bf16_f32 v120, v124, v125
	v_cvt_pk_bf16_f32 v121, v126, v127
	v_cvt_pk_bf16_f32 v122, v122, v123
	v_cvt_pk_bf16_f32 v123, v160, v161
	v_lshl_add_u64 v[124:125], v[166:167], 0, s[18:19]
	global_store_dwordx4 v[124:125], v[120:123], off sc1 nt
	s_nop 1
	ds_read_b32 v124, v147 offset:64
	v_or_b32_e32 v120, 16, v146
	v_mad_i64_i32 v[120:121], s[0:1], v120, s56, v[148:149]
	v_lshl_add_u64 v[126:127], v[120:121], 0, v[150:151]
	s_waitcnt lgkmcnt(0)
	v_pk_mul_f32 v[122:123], v[70:71], v[124:125] op_sel_hi:[1,0]
	v_pk_mul_f32 v[120:121], v[68:69], v[124:125] op_sel_hi:[1,0]
	v_pk_mul_f32 v[160:161], v[58:59], v[124:125] op_sel_hi:[1,0]
	v_pk_mul_f32 v[162:163], v[56:57], v[124:125] op_sel_hi:[1,0]
	v_cvt_pk_bf16_f32 v120, v120, v121
	v_cvt_pk_bf16_f32 v121, v122, v123
	v_cvt_pk_bf16_f32 v122, v162, v163
	v_cvt_pk_bf16_f32 v123, v160, v161
	global_store_dwordx4 v[126:127], v[120:123], off sc1 nt
	s_nop 1
	v_pk_mul_f32 v[118:119], v[118:119], v[124:125] op_sel_hi:[1,0]
	v_pk_mul_f32 v[116:117], v[116:117], v[124:125] op_sel_hi:[1,0]
	v_pk_mul_f32 v[120:121], v[114:115], v[124:125] op_sel_hi:[1,0]
	v_pk_mul_f32 v[114:115], v[112:113], v[124:125] op_sel_hi:[1,0]
	v_cvt_pk_bf16_f32 v112, v116, v117
	v_cvt_pk_bf16_f32 v113, v118, v119
	v_cvt_pk_bf16_f32 v114, v114, v115
	v_cvt_pk_bf16_f32 v115, v120, v121
	v_lshl_add_u64 v[116:117], v[126:127], 0, s[18:19]
	global_store_dwordx4 v[116:117], v[112:115], off sc1 nt
	s_nop 1
	ds_read_b32 v116, v147 offset:128
	v_or_b32_e32 v112, 32, v146
	v_mad_i64_i32 v[112:113], s[0:1], v112, s56, v[148:149]
	v_lshl_add_u64 v[118:119], v[112:113], 0, v[150:151]
	s_waitcnt lgkmcnt(0)
	v_pk_mul_f32 v[114:115], v[54:55], v[116:117] op_sel_hi:[1,0]
	v_pk_mul_f32 v[112:113], v[52:53], v[116:117] op_sel_hi:[1,0]
	v_pk_mul_f32 v[120:121], v[50:51], v[116:117] op_sel_hi:[1,0]
	v_pk_mul_f32 v[122:123], v[48:49], v[116:117] op_sel_hi:[1,0]
	v_cvt_pk_bf16_f32 v112, v112, v113
	v_cvt_pk_bf16_f32 v113, v114, v115
	v_cvt_pk_bf16_f32 v114, v122, v123
	v_cvt_pk_bf16_f32 v115, v120, v121
	global_store_dwordx4 v[118:119], v[112:115], off sc1 nt
	s_nop 1
	v_pk_mul_f32 v[110:111], v[110:111], v[116:117] op_sel_hi:[1,0]
	v_pk_mul_f32 v[108:109], v[108:109], v[116:117] op_sel_hi:[1,0]
	v_pk_mul_f32 v[112:113], v[106:107], v[116:117] op_sel_hi:[1,0]
	v_pk_mul_f32 v[106:107], v[104:105], v[116:117] op_sel_hi:[1,0]
	v_cvt_pk_bf16_f32 v104, v108, v109
	v_cvt_pk_bf16_f32 v105, v110, v111
	v_cvt_pk_bf16_f32 v106, v106, v107
	v_cvt_pk_bf16_f32 v107, v112, v113
	v_lshl_add_u64 v[108:109], v[118:119], 0, s[18:19]
	global_store_dwordx4 v[108:109], v[104:107], off sc1 nt
	s_nop 1
	ds_read_b32 v108, v147 offset:192
	v_or_b32_e32 v104, 48, v146
	v_mad_i64_i32 v[104:105], s[0:1], v104, s56, v[148:149]
	v_lshl_add_u64 v[110:111], v[104:105], 0, v[150:151]
	s_waitcnt lgkmcnt(0)
	v_pk_mul_f32 v[106:107], v[38:39], v[108:109] op_sel_hi:[1,0]
	v_pk_mul_f32 v[104:105], v[36:37], v[108:109] op_sel_hi:[1,0]
	v_pk_mul_f32 v[112:113], v[34:35], v[108:109] op_sel_hi:[1,0]
	v_pk_mul_f32 v[114:115], v[32:33], v[108:109] op_sel_hi:[1,0]
	v_cvt_pk_bf16_f32 v104, v104, v105
	v_cvt_pk_bf16_f32 v105, v106, v107
	v_cvt_pk_bf16_f32 v106, v114, v115
	v_cvt_pk_bf16_f32 v107, v112, v113
	global_store_dwordx4 v[110:111], v[104:107], off sc1 nt
	s_nop 1
	v_pk_mul_f32 v[102:103], v[102:103], v[108:109] op_sel_hi:[1,0]
	v_pk_mul_f32 v[100:101], v[100:101], v[108:109] op_sel_hi:[1,0]
	v_pk_mul_f32 v[104:105], v[98:99], v[108:109] op_sel_hi:[1,0]
	v_pk_mul_f32 v[98:99], v[96:97], v[108:109] op_sel_hi:[1,0]
	v_cvt_pk_bf16_f32 v96, v100, v101
	v_cvt_pk_bf16_f32 v97, v102, v103
	v_cvt_pk_bf16_f32 v98, v98, v99
	v_cvt_pk_bf16_f32 v99, v104, v105
	v_lshl_add_u64 v[100:101], v[110:111], 0, s[18:19]
	global_store_dwordx4 v[100:101], v[96:99], off sc1 nt
	s_nop 1
	ds_read_b32 v100, v147 offset:512
	v_add_u32_e32 v96, 0x80, v146
	v_mad_i64_i32 v[96:97], s[0:1], v96, s56, v[148:149]
	v_lshl_add_u64 v[102:103], v[96:97], 0, v[150:151]
	s_waitcnt lgkmcnt(0)
	v_pk_mul_f32 v[98:99], v[30:31], v[100:101] op_sel_hi:[1,0]
	v_pk_mul_f32 v[96:97], v[28:29], v[100:101] op_sel_hi:[1,0]
	v_pk_mul_f32 v[104:105], v[26:27], v[100:101] op_sel_hi:[1,0]
	v_pk_mul_f32 v[106:107], v[24:25], v[100:101] op_sel_hi:[1,0]
	v_cvt_pk_bf16_f32 v96, v96, v97
	v_cvt_pk_bf16_f32 v97, v98, v99
	v_cvt_pk_bf16_f32 v98, v106, v107
	v_cvt_pk_bf16_f32 v99, v104, v105
	global_store_dwordx4 v[102:103], v[96:99], off sc1 nt
	s_nop 1
	v_pk_mul_f32 v[94:95], v[94:95], v[100:101] op_sel_hi:[1,0]
	v_pk_mul_f32 v[92:93], v[92:93], v[100:101] op_sel_hi:[1,0]
	v_pk_mul_f32 v[96:97], v[90:91], v[100:101] op_sel_hi:[1,0]
	v_pk_mul_f32 v[90:91], v[88:89], v[100:101] op_sel_hi:[1,0]
	v_cvt_pk_bf16_f32 v88, v92, v93
	v_cvt_pk_bf16_f32 v89, v94, v95
	v_cvt_pk_bf16_f32 v90, v90, v91
	v_cvt_pk_bf16_f32 v91, v96, v97
	v_lshl_add_u64 v[92:93], v[102:103], 0, s[18:19]
	global_store_dwordx4 v[92:93], v[88:91], off sc1 nt
	s_nop 1
	ds_read_b32 v92, v147 offset:576
	v_add_u32_e32 v88, 0x90, v146
	v_mad_i64_i32 v[88:89], s[0:1], v88, s56, v[148:149]
	v_lshl_add_u64 v[94:95], v[88:89], 0, v[150:151]
	s_waitcnt lgkmcnt(0)
	v_pk_mul_f32 v[90:91], v[22:23], v[92:93] op_sel_hi:[1,0]
	v_pk_mul_f32 v[88:89], v[20:21], v[92:93] op_sel_hi:[1,0]
	v_pk_mul_f32 v[96:97], v[18:19], v[92:93] op_sel_hi:[1,0]
	v_pk_mul_f32 v[98:99], v[16:17], v[92:93] op_sel_hi:[1,0]
	v_cvt_pk_bf16_f32 v88, v88, v89
	v_cvt_pk_bf16_f32 v89, v90, v91
	v_cvt_pk_bf16_f32 v90, v98, v99
	v_cvt_pk_bf16_f32 v91, v96, v97
	global_store_dwordx4 v[94:95], v[88:91], off sc1 nt
	s_nop 1
	v_pk_mul_f32 v[86:87], v[86:87], v[92:93] op_sel_hi:[1,0]
	v_pk_mul_f32 v[84:85], v[84:85], v[92:93] op_sel_hi:[1,0]
	v_pk_mul_f32 v[88:89], v[82:83], v[92:93] op_sel_hi:[1,0]
	v_pk_mul_f32 v[82:83], v[80:81], v[92:93] op_sel_hi:[1,0]
	v_cvt_pk_bf16_f32 v80, v84, v85
	v_cvt_pk_bf16_f32 v81, v86, v87
	v_cvt_pk_bf16_f32 v82, v82, v83
	v_cvt_pk_bf16_f32 v83, v88, v89
	v_lshl_add_u64 v[84:85], v[94:95], 0, s[18:19]
	global_store_dwordx4 v[84:85], v[80:83], off sc1 nt
	s_nop 1
	ds_read_b32 v84, v147 offset:640
	v_add_u32_e32 v80, 0xa0, v146
	v_mad_i64_i32 v[80:81], s[0:1], v80, s56, v[148:149]
	v_lshl_add_u64 v[86:87], v[80:81], 0, v[150:151]
	s_waitcnt lgkmcnt(0)
	v_pk_mul_f32 v[82:83], v[14:15], v[84:85] op_sel_hi:[1,0]
	v_pk_mul_f32 v[80:81], v[12:13], v[84:85] op_sel_hi:[1,0]
	v_pk_mul_f32 v[88:89], v[10:11], v[84:85] op_sel_hi:[1,0]
	v_pk_mul_f32 v[90:91], v[8:9], v[84:85] op_sel_hi:[1,0]
	v_cvt_pk_bf16_f32 v80, v80, v81
	v_cvt_pk_bf16_f32 v81, v82, v83
	v_cvt_pk_bf16_f32 v82, v90, v91
	v_cvt_pk_bf16_f32 v83, v88, v89
	global_store_dwordx4 v[86:87], v[80:83], off sc1 nt
	s_nop 1
	v_pk_mul_f32 v[66:67], v[66:67], v[84:85] op_sel_hi:[1,0]
	v_pk_mul_f32 v[64:65], v[64:65], v[84:85] op_sel_hi:[1,0]
	v_pk_mul_f32 v[80:81], v[62:63], v[84:85] op_sel_hi:[1,0]
	v_pk_mul_f32 v[62:63], v[60:61], v[84:85] op_sel_hi:[1,0]
	v_cvt_pk_bf16_f32 v60, v64, v65
	v_cvt_pk_bf16_f32 v61, v66, v67
	v_cvt_pk_bf16_f32 v62, v62, v63
	v_cvt_pk_bf16_f32 v63, v80, v81
	v_lshl_add_u64 v[64:65], v[86:87], 0, s[18:19]
	global_store_dwordx4 v[64:65], v[60:63], off sc1 nt
	s_nop 1
	ds_read_b32 v64, v147 offset:704
	v_add_u32_e32 v60, 0xb0, v146
	v_mad_i64_i32 v[60:61], s[0:1], v60, s56, v[148:149]
	v_lshl_add_u64 v[66:67], v[60:61], 0, v[150:151]
	s_waitcnt lgkmcnt(0)
	v_pk_mul_f32 v[62:63], v[6:7], v[64:65] op_sel_hi:[1,0]
	v_pk_mul_f32 v[60:61], v[4:5], v[64:65] op_sel_hi:[1,0]
	v_pk_mul_f32 v[80:81], v[2:3], v[64:65] op_sel_hi:[1,0]
	v_pk_mul_f32 v[82:83], v[0:1], v[64:65] op_sel_hi:[1,0]
	v_cvt_pk_bf16_f32 v60, v60, v61
	v_cvt_pk_bf16_f32 v61, v62, v63
	v_cvt_pk_bf16_f32 v62, v82, v83
	v_cvt_pk_bf16_f32 v63, v80, v81
	global_store_dwordx4 v[66:67], v[60:63], off sc1 nt
	s_nop 1
	v_pk_mul_f32 v[46:47], v[46:47], v[64:65] op_sel_hi:[1,0]
	v_pk_mul_f32 v[44:45], v[44:45], v[64:65] op_sel_hi:[1,0]
	v_pk_mul_f32 v[60:61], v[42:43], v[64:65] op_sel_hi:[1,0]
	v_pk_mul_f32 v[42:43], v[40:41], v[64:65] op_sel_hi:[1,0]
	v_cvt_pk_bf16_f32 v40, v44, v45
	v_cvt_pk_bf16_f32 v41, v46, v47
	v_cvt_pk_bf16_f32 v42, v42, v43
	v_cvt_pk_bf16_f32 v43, v60, v61
	v_lshl_add_u64 v[44:45], v[66:67], 0, s[18:19]
	global_store_dwordx4 v[44:45], v[40:43], off sc1 nt
	s_nop 1
	s_cbranch_execnz .LBB0_1197

.LBB0_2793:
	s_cmp_eq_u32 s75, -1
	v_lshl_add_u32 v146, s48, 8, v150
	s_cbranch_scc1 .LBB0_2796
	v_lshl_add_u32 v157, s74, 10, v152
	ds_read_b32 v162, v157
	v_lshl_or_b32 v148, s75, 8, v153
	v_ashrrev_i32_e32 v147, 31, v146
	v_ashrrev_i32_e32 v149, 31, v148
	v_lshlrev_b64 v[158:159], 13, v[146:147]
	v_lshl_add_u64 v[158:159], s[8:9], 0, v[158:159]
	v_lshlrev_b64 v[164:165], 1, v[148:149]
	s_waitcnt lgkmcnt(0)
	v_pk_mul_f32 v[172:173], v[64:65], v[162:163] op_sel_hi:[1,0]
	v_lshl_add_u64 v[148:149], v[158:159], 0, v[164:165]
	v_pk_mul_f32 v[158:159], v[70:71], v[162:163] op_sel_hi:[1,0]
	v_pk_mul_f32 v[160:161], v[68:69], v[162:163] op_sel_hi:[1,0]
	v_pk_mul_f32 v[166:167], v[66:67], v[162:163] op_sel_hi:[1,0]
	v_max_f32_e32 v163, 0, v173
	v_mul_f32_e32 v163, v163, v163
	v_max_f32_e32 v147, 0, v160
	v_max_f32_e32 v161, 0, v161
	v_max_f32_e32 v158, 0, v158
	v_pk_mul_f32 v[122:123], v[122:123], v[162:163] op_sel_hi:[1,0]
	v_pk_mul_f32 v[120:121], v[120:121], v[162:163] op_sel_hi:[1,0]
	v_max_f32_e32 v160, 0, v172
	v_mul_f32_e32 v147, v147, v147
	v_mul_f32_e32 v161, v161, v161
	v_max_f32_e32 v166, 0, v166
	v_mul_f32_e32 v169, v158, v158
	v_max_f32_e32 v158, 0, v159
	v_max_f32_e32 v159, 0, v167
	v_pk_mul_f32 v[126:127], v[126:127], v[162:163] op_sel_hi:[1,0]
	v_pk_mul_f32 v[124:125], v[124:125], v[162:163] op_sel_hi:[1,0]
	v_max_f32_e32 v120, 0, v120
	v_max_f32_e32 v121, 0, v121
	v_max_f32_e32 v122, 0, v122
	v_mul_f32_e32 v160, v160, v160
	v_mul_f32_e32 v166, v166, v166
	v_mul_f32_e32 v167, v158, v158
	v_mul_f32_e32 v171, v159, v159
	v_cvt_pk_bf16_f32 v158, v147, v161
	v_max_f32_e32 v124, 0, v124
	v_mul_f32_e32 v147, v120, v120
	v_max_f32_e32 v120, 0, v125
	v_mul_f32_e32 v125, v121, v121
	v_max_f32_e32 v121, 0, v126
	v_mul_f32_e32 v126, v122, v122
	v_max_f32_e32 v122, 0, v127
	v_max_f32_e32 v123, 0, v123
	v_cvt_pk_bf16_f32 v159, v169, v167
	v_cvt_pk_bf16_f32 v160, v160, v163
	v_cvt_pk_bf16_f32 v161, v166, v171
	global_store_dwordx4 v[148:149], v[158:161], off sc1 nt
	s_nop 1
	v_mul_f32_e32 v124, v124, v124
	v_mul_f32_e32 v120, v120, v120
	v_mul_f32_e32 v121, v121, v121
	v_mul_f32_e32 v122, v122, v122
	v_mul_f32_e32 v123, v123, v123
	v_cvt_pk_bf16_f32 v120, v124, v120
	v_cvt_pk_bf16_f32 v121, v121, v122
	v_cvt_pk_bf16_f32 v122, v147, v125
	v_cvt_pk_bf16_f32 v123, v126, v123
	v_lshl_add_u64 v[124:125], v[148:149], 0, s[18:19]
	global_store_dwordx4 v[124:125], v[120:123], off sc1 nt
	s_nop 1
	ds_read_b32 v124, v157 offset:64
	v_or_b32_e32 v120, 16, v146
	v_ashrrev_i32_e32 v121, 31, v120
	v_lshlrev_b64 v[120:121], 13, v[120:121]
	v_lshl_add_u64 v[120:121], s[8:9], 0, v[120:121]
	s_waitcnt lgkmcnt(0)
	v_pk_mul_f32 v[160:161], v[56:57], v[124:125] op_sel_hi:[1,0]
	v_lshl_add_u64 v[126:127], v[120:121], 0, v[164:165]
	v_pk_mul_f32 v[120:121], v[62:63], v[124:125] op_sel_hi:[1,0]
	v_pk_mul_f32 v[122:123], v[60:61], v[124:125] op_sel_hi:[1,0]
	v_pk_mul_f32 v[158:159], v[58:59], v[124:125] op_sel_hi:[1,0]
	v_max_f32_e32 v125, 0, v160
	v_max_f32_e32 v122, 0, v122
	v_mul_f32_e32 v125, v125, v125
	v_max_f32_e32 v123, 0, v123
	v_max_f32_e32 v120, 0, v120
	v_mul_f32_e32 v122, v122, v122
	v_max_f32_e32 v147, 0, v161
	v_mul_f32_e32 v123, v123, v123
	v_max_f32_e32 v158, 0, v158
	v_mul_f32_e32 v160, v120, v120
	v_max_f32_e32 v120, 0, v121
	v_max_f32_e32 v121, 0, v159
	v_pk_mul_f32 v[114:115], v[114:115], v[124:125] op_sel_hi:[1,0]
	v_pk_mul_f32 v[112:113], v[112:113], v[124:125] op_sel_hi:[1,0]
	v_mul_f32_e32 v147, v147, v147
	v_mul_f32_e32 v158, v158, v158
	v_mul_f32_e32 v159, v120, v120
	v_mul_f32_e32 v161, v121, v121
	v_cvt_pk_bf16_f32 v120, v122, v123
	v_pk_mul_f32 v[118:119], v[118:119], v[124:125] op_sel_hi:[1,0]
	v_pk_mul_f32 v[116:117], v[116:117], v[124:125] op_sel_hi:[1,0]
	v_max_f32_e32 v112, 0, v112
	v_max_f32_e32 v113, 0, v113
	v_max_f32_e32 v114, 0, v114
	v_cvt_pk_bf16_f32 v121, v160, v159
	v_cvt_pk_bf16_f32 v122, v125, v147
	v_cvt_pk_bf16_f32 v123, v158, v161
	global_store_dwordx4 v[126:127], v[120:123], off sc1 nt
	s_nop 1
	v_max_f32_e32 v116, 0, v116
	v_mul_f32_e32 v120, v112, v112
	v_max_f32_e32 v112, 0, v117
	v_mul_f32_e32 v117, v113, v113
	v_max_f32_e32 v113, 0, v118
	v_mul_f32_e32 v118, v114, v114
	v_max_f32_e32 v114, 0, v119
	v_max_f32_e32 v115, 0, v115
	v_mul_f32_e32 v116, v116, v116
	v_mul_f32_e32 v112, v112, v112
	v_mul_f32_e32 v113, v113, v113
	v_mul_f32_e32 v114, v114, v114
	v_mul_f32_e32 v115, v115, v115
	v_cvt_pk_bf16_f32 v112, v116, v112
	v_cvt_pk_bf16_f32 v113, v113, v114
	v_cvt_pk_bf16_f32 v114, v120, v117
	v_cvt_pk_bf16_f32 v115, v118, v115
	v_lshl_add_u64 v[116:117], v[126:127], 0, s[18:19]
	global_store_dwordx4 v[116:117], v[112:115], off sc1 nt
	s_nop 1
	ds_read_b32 v116, v157 offset:128
	v_or_b32_e32 v112, 32, v146
	v_ashrrev_i32_e32 v113, 31, v112
	v_lshlrev_b64 v[112:113], 13, v[112:113]
	v_lshl_add_u64 v[112:113], s[8:9], 0, v[112:113]
	s_waitcnt lgkmcnt(0)
	v_pk_mul_f32 v[122:123], v[40:41], v[116:117] op_sel_hi:[1,0]
	v_lshl_add_u64 v[118:119], v[112:113], 0, v[164:165]
	v_pk_mul_f32 v[112:113], v[50:51], v[116:117] op_sel_hi:[1,0]
	v_pk_mul_f32 v[114:115], v[48:49], v[116:117] op_sel_hi:[1,0]
	v_pk_mul_f32 v[120:121], v[42:43], v[116:117] op_sel_hi:[1,0]
	v_max_f32_e32 v117, 0, v122
	v_max_f32_e32 v114, 0, v114
	v_mul_f32_e32 v117, v117, v117
	v_max_f32_e32 v115, 0, v115
	v_max_f32_e32 v112, 0, v112
	v_mul_f32_e32 v114, v114, v114
	v_max_f32_e32 v122, 0, v123
	v_mul_f32_e32 v115, v115, v115
	v_max_f32_e32 v120, 0, v120
	v_mul_f32_e32 v123, v112, v112
	v_max_f32_e32 v112, 0, v113
	v_max_f32_e32 v113, 0, v121
	v_pk_mul_f32 v[106:107], v[106:107], v[116:117] op_sel_hi:[1,0]
	v_pk_mul_f32 v[104:105], v[104:105], v[116:117] op_sel_hi:[1,0]
	v_mul_f32_e32 v122, v122, v122
	v_mul_f32_e32 v120, v120, v120
	v_mul_f32_e32 v121, v112, v112
	v_mul_f32_e32 v124, v113, v113
	v_cvt_pk_bf16_f32 v112, v114, v115
	v_pk_mul_f32 v[110:111], v[110:111], v[116:117] op_sel_hi:[1,0]
	v_pk_mul_f32 v[108:109], v[108:109], v[116:117] op_sel_hi:[1,0]
	v_max_f32_e32 v104, 0, v104
	v_max_f32_e32 v105, 0, v105
	v_max_f32_e32 v106, 0, v106
	v_cvt_pk_bf16_f32 v113, v123, v121
	v_cvt_pk_bf16_f32 v114, v117, v122
	v_cvt_pk_bf16_f32 v115, v120, v124
	global_store_dwordx4 v[118:119], v[112:115], off sc1 nt
	s_nop 1
	v_max_f32_e32 v108, 0, v108
	v_mul_f32_e32 v112, v104, v104
	v_max_f32_e32 v104, 0, v109
	v_mul_f32_e32 v109, v105, v105
	v_max_f32_e32 v105, 0, v110
	v_mul_f32_e32 v110, v106, v106
	v_max_f32_e32 v106, 0, v111
	v_max_f32_e32 v107, 0, v107
	v_mul_f32_e32 v108, v108, v108
	v_mul_f32_e32 v104, v104, v104
	v_mul_f32_e32 v105, v105, v105
	v_mul_f32_e32 v106, v106, v106
	v_mul_f32_e32 v107, v107, v107
	v_cvt_pk_bf16_f32 v104, v108, v104
	v_cvt_pk_bf16_f32 v105, v105, v106
	v_cvt_pk_bf16_f32 v106, v112, v109
	v_cvt_pk_bf16_f32 v107, v110, v107
	v_lshl_add_u64 v[108:109], v[118:119], 0, s[18:19]
	global_store_dwordx4 v[108:109], v[104:107], off sc1 nt
	s_nop 1
	ds_read_b32 v108, v157 offset:192
	v_or_b32_e32 v104, 48, v146
	v_ashrrev_i32_e32 v105, 31, v104
	v_lshlrev_b64 v[104:105], 13, v[104:105]
	v_lshl_add_u64 v[104:105], s[8:9], 0, v[104:105]
	s_waitcnt lgkmcnt(0)
	v_pk_mul_f32 v[114:115], v[32:33], v[108:109] op_sel_hi:[1,0]
	v_lshl_add_u64 v[110:111], v[104:105], 0, v[164:165]
	v_pk_mul_f32 v[104:105], v[38:39], v[108:109] op_sel_hi:[1,0]
	v_pk_mul_f32 v[106:107], v[36:37], v[108:109] op_sel_hi:[1,0]
	v_pk_mul_f32 v[112:113], v[34:35], v[108:109] op_sel_hi:[1,0]
	v_max_f32_e32 v109, 0, v114
	v_max_f32_e32 v106, 0, v106
	v_mul_f32_e32 v109, v109, v109
	v_max_f32_e32 v107, 0, v107
	v_max_f32_e32 v104, 0, v104
	v_mul_f32_e32 v106, v106, v106
	v_max_f32_e32 v114, 0, v115
	v_mul_f32_e32 v107, v107, v107
	v_max_f32_e32 v112, 0, v112
	v_mul_f32_e32 v115, v104, v104
	v_max_f32_e32 v104, 0, v105
	v_max_f32_e32 v105, 0, v113
	v_pk_mul_f32 v[98:99], v[98:99], v[108:109] op_sel_hi:[1,0]
	v_pk_mul_f32 v[96:97], v[96:97], v[108:109] op_sel_hi:[1,0]
	v_mul_f32_e32 v114, v114, v114
	v_mul_f32_e32 v112, v112, v112
	v_mul_f32_e32 v113, v104, v104
	v_mul_f32_e32 v116, v105, v105
	v_cvt_pk_bf16_f32 v104, v106, v107
	v_pk_mul_f32 v[102:103], v[102:103], v[108:109] op_sel_hi:[1,0]
	v_pk_mul_f32 v[100:101], v[100:101], v[108:109] op_sel_hi:[1,0]
	v_max_f32_e32 v96, 0, v96
	v_max_f32_e32 v97, 0, v97
	v_max_f32_e32 v98, 0, v98
	v_cvt_pk_bf16_f32 v105, v115, v113
	v_cvt_pk_bf16_f32 v106, v109, v114
	v_cvt_pk_bf16_f32 v107, v112, v116
	global_store_dwordx4 v[110:111], v[104:107], off sc1 nt
	s_nop 1
	v_max_f32_e32 v100, 0, v100
	v_mul_f32_e32 v104, v96, v96
	v_max_f32_e32 v96, 0, v101
	v_mul_f32_e32 v101, v97, v97
	v_max_f32_e32 v97, 0, v102
	v_mul_f32_e32 v102, v98, v98
	v_max_f32_e32 v98, 0, v103
	v_max_f32_e32 v99, 0, v99
	v_mul_f32_e32 v100, v100, v100
	v_mul_f32_e32 v96, v96, v96
	v_mul_f32_e32 v97, v97, v97
	v_mul_f32_e32 v98, v98, v98
	v_mul_f32_e32 v99, v99, v99
	v_cvt_pk_bf16_f32 v96, v100, v96
	v_cvt_pk_bf16_f32 v97, v97, v98
	v_cvt_pk_bf16_f32 v98, v104, v101
	v_cvt_pk_bf16_f32 v99, v102, v99
	v_lshl_add_u64 v[100:101], v[110:111], 0, s[18:19]
	global_store_dwordx4 v[100:101], v[96:99], off sc1 nt
	s_nop 1
	ds_read_b32 v100, v157 offset:512
	v_lshl_add_u64 v[102:103], v[148:149], 0, s[20:21]
	s_waitcnt lgkmcnt(0)
	v_pk_mul_f32 v[106:107], v[24:25], v[100:101] op_sel_hi:[1,0]
	v_pk_mul_f32 v[96:97], v[30:31], v[100:101] op_sel_hi:[1,0]
	v_pk_mul_f32 v[98:99], v[28:29], v[100:101] op_sel_hi:[1,0]
	v_pk_mul_f32 v[104:105], v[26:27], v[100:101] op_sel_hi:[1,0]
	v_max_f32_e32 v101, 0, v106
	v_max_f32_e32 v98, 0, v98
	v_mul_f32_e32 v101, v101, v101
	v_max_f32_e32 v99, 0, v99
	v_max_f32_e32 v96, 0, v96
	v_mul_f32_e32 v98, v98, v98
	v_max_f32_e32 v106, 0, v107
	v_mul_f32_e32 v99, v99, v99
	v_max_f32_e32 v104, 0, v104
	v_mul_f32_e32 v107, v96, v96
	v_max_f32_e32 v96, 0, v97
	v_max_f32_e32 v97, 0, v105
	v_pk_mul_f32 v[90:91], v[90:91], v[100:101] op_sel_hi:[1,0]
	v_pk_mul_f32 v[88:89], v[88:89], v[100:101] op_sel_hi:[1,0]
	v_mul_f32_e32 v106, v106, v106
	v_mul_f32_e32 v104, v104, v104
	v_mul_f32_e32 v105, v96, v96
	v_mul_f32_e32 v108, v97, v97
	v_cvt_pk_bf16_f32 v96, v98, v99
	v_pk_mul_f32 v[94:95], v[94:95], v[100:101] op_sel_hi:[1,0]
	v_pk_mul_f32 v[92:93], v[92:93], v[100:101] op_sel_hi:[1,0]
	v_max_f32_e32 v88, 0, v88
	v_max_f32_e32 v89, 0, v89
	v_max_f32_e32 v90, 0, v90
	v_cvt_pk_bf16_f32 v97, v107, v105
	v_cvt_pk_bf16_f32 v98, v101, v106
	v_cvt_pk_bf16_f32 v99, v104, v108
	global_store_dwordx4 v[102:103], v[96:99], off sc1 nt
	s_nop 1
	v_max_f32_e32 v92, 0, v92
	v_mul_f32_e32 v96, v88, v88
	v_max_f32_e32 v88, 0, v93
	v_mul_f32_e32 v93, v89, v89
	v_max_f32_e32 v89, 0, v94
	v_mul_f32_e32 v94, v90, v90
	v_max_f32_e32 v90, 0, v95
	v_max_f32_e32 v91, 0, v91
	v_mul_f32_e32 v92, v92, v92
	v_mul_f32_e32 v88, v88, v88
	v_mul_f32_e32 v89, v89, v89
	v_mul_f32_e32 v90, v90, v90
	v_mul_f32_e32 v91, v91, v91
	v_cvt_pk_bf16_f32 v88, v92, v88
	v_cvt_pk_bf16_f32 v89, v89, v90
	v_cvt_pk_bf16_f32 v90, v96, v93
	v_cvt_pk_bf16_f32 v91, v94, v91
	v_lshl_add_u64 v[92:93], v[148:149], 0, s[22:23]
	global_store_dwordx4 v[92:93], v[88:91], off sc1 nt
	s_nop 1
	ds_read_b32 v92, v157 offset:576
	v_lshl_add_u64 v[94:95], v[148:149], 0, s[24:25]
	s_waitcnt lgkmcnt(0)
	v_pk_mul_f32 v[98:99], v[16:17], v[92:93] op_sel_hi:[1,0]
	v_pk_mul_f32 v[88:89], v[22:23], v[92:93] op_sel_hi:[1,0]
	v_pk_mul_f32 v[90:91], v[20:21], v[92:93] op_sel_hi:[1,0]
	v_pk_mul_f32 v[96:97], v[18:19], v[92:93] op_sel_hi:[1,0]
	v_max_f32_e32 v93, 0, v98
	v_max_f32_e32 v90, 0, v90
	v_mul_f32_e32 v93, v93, v93
	v_max_f32_e32 v91, 0, v91
	v_max_f32_e32 v88, 0, v88
	v_mul_f32_e32 v90, v90, v90
	v_max_f32_e32 v98, 0, v99
	v_mul_f32_e32 v91, v91, v91
	v_max_f32_e32 v96, 0, v96
	v_mul_f32_e32 v99, v88, v88
	v_max_f32_e32 v88, 0, v89
	v_max_f32_e32 v89, 0, v97
	v_pk_mul_f32 v[82:83], v[82:83], v[92:93] op_sel_hi:[1,0]
	v_pk_mul_f32 v[80:81], v[80:81], v[92:93] op_sel_hi:[1,0]
	v_mul_f32_e32 v98, v98, v98
	v_mul_f32_e32 v96, v96, v96
	v_mul_f32_e32 v97, v88, v88
	v_mul_f32_e32 v100, v89, v89
	v_cvt_pk_bf16_f32 v88, v90, v91
	v_pk_mul_f32 v[86:87], v[86:87], v[92:93] op_sel_hi:[1,0]
	v_pk_mul_f32 v[84:85], v[84:85], v[92:93] op_sel_hi:[1,0]
	v_max_f32_e32 v80, 0, v80
	v_max_f32_e32 v81, 0, v81
	v_max_f32_e32 v82, 0, v82
	v_cvt_pk_bf16_f32 v89, v99, v97
	v_cvt_pk_bf16_f32 v90, v93, v98
	v_cvt_pk_bf16_f32 v91, v96, v100
	global_store_dwordx4 v[94:95], v[88:91], off sc1 nt
	s_nop 1
	v_max_f32_e32 v84, 0, v84
	v_mul_f32_e32 v88, v80, v80
	v_max_f32_e32 v80, 0, v85
	v_mul_f32_e32 v85, v81, v81
	v_max_f32_e32 v81, 0, v86
	v_mul_f32_e32 v86, v82, v82
	v_max_f32_e32 v82, 0, v87
	v_max_f32_e32 v83, 0, v83
	v_mul_f32_e32 v84, v84, v84
	v_mul_f32_e32 v80, v80, v80
	v_mul_f32_e32 v81, v81, v81
	v_mul_f32_e32 v82, v82, v82
	v_mul_f32_e32 v83, v83, v83
	v_cvt_pk_bf16_f32 v80, v84, v80
	v_cvt_pk_bf16_f32 v81, v81, v82
	v_cvt_pk_bf16_f32 v82, v88, v85
	v_cvt_pk_bf16_f32 v83, v86, v83
	v_lshl_add_u64 v[84:85], v[148:149], 0, s[26:27]
	global_store_dwordx4 v[84:85], v[80:83], off sc1 nt
	s_nop 1
	ds_read_b32 v84, v157 offset:640
	v_lshl_add_u64 v[86:87], v[148:149], 0, s[28:29]
	s_waitcnt lgkmcnt(0)
	v_pk_mul_f32 v[90:91], v[8:9], v[84:85] op_sel_hi:[1,0]
	v_pk_mul_f32 v[80:81], v[14:15], v[84:85] op_sel_hi:[1,0]
	v_pk_mul_f32 v[82:83], v[12:13], v[84:85] op_sel_hi:[1,0]
	v_pk_mul_f32 v[88:89], v[10:11], v[84:85] op_sel_hi:[1,0]
	v_max_f32_e32 v85, 0, v90
	v_max_f32_e32 v82, 0, v82
	v_mul_f32_e32 v85, v85, v85
	v_max_f32_e32 v83, 0, v83
	v_max_f32_e32 v80, 0, v80
	v_mul_f32_e32 v82, v82, v82
	v_max_f32_e32 v90, 0, v91
	v_mul_f32_e32 v83, v83, v83
	v_max_f32_e32 v88, 0, v88
	v_mul_f32_e32 v91, v80, v80
	v_max_f32_e32 v80, 0, v81
	v_max_f32_e32 v81, 0, v89
	v_pk_mul_f32 v[74:75], v[74:75], v[84:85] op_sel_hi:[1,0]
	v_pk_mul_f32 v[72:73], v[72:73], v[84:85] op_sel_hi:[1,0]
	v_mul_f32_e32 v90, v90, v90
	v_mul_f32_e32 v88, v88, v88
	v_mul_f32_e32 v89, v80, v80
	v_mul_f32_e32 v92, v81, v81
	v_cvt_pk_bf16_f32 v80, v82, v83
	v_pk_mul_f32 v[78:79], v[78:79], v[84:85] op_sel_hi:[1,0]
	v_pk_mul_f32 v[76:77], v[76:77], v[84:85] op_sel_hi:[1,0]
	v_max_f32_e32 v72, 0, v72
	v_max_f32_e32 v73, 0, v73
	v_max_f32_e32 v74, 0, v74
	v_cvt_pk_bf16_f32 v81, v91, v89
	v_cvt_pk_bf16_f32 v82, v85, v90
	v_cvt_pk_bf16_f32 v83, v88, v92
	global_store_dwordx4 v[86:87], v[80:83], off sc1 nt
	s_nop 1
	v_max_f32_e32 v76, 0, v76
	v_mul_f32_e32 v80, v72, v72
	v_max_f32_e32 v72, 0, v77
	v_mul_f32_e32 v77, v73, v73
	v_max_f32_e32 v73, 0, v78
	v_mul_f32_e32 v78, v74, v74
	v_max_f32_e32 v74, 0, v79
	v_max_f32_e32 v75, 0, v75
	v_mul_f32_e32 v76, v76, v76
	v_mul_f32_e32 v72, v72, v72
	v_mul_f32_e32 v73, v73, v73
	v_mul_f32_e32 v74, v74, v74
	v_mul_f32_e32 v75, v75, v75
	v_cvt_pk_bf16_f32 v72, v76, v72
	v_cvt_pk_bf16_f32 v73, v73, v74
	v_cvt_pk_bf16_f32 v74, v80, v77
	v_cvt_pk_bf16_f32 v75, v78, v75
	v_lshl_add_u64 v[76:77], v[148:149], 0, s[30:31]
	global_store_dwordx4 v[76:77], v[72:75], off sc1 nt
	s_nop 1
	ds_read_b32 v76, v157 offset:704
	v_lshl_add_u64 v[78:79], v[148:149], 0, s[34:35]
	s_waitcnt lgkmcnt(0)
	v_pk_mul_f32 v[82:83], v[0:1], v[76:77] op_sel_hi:[1,0]
	v_pk_mul_f32 v[72:73], v[6:7], v[76:77] op_sel_hi:[1,0]
	v_pk_mul_f32 v[74:75], v[4:5], v[76:77] op_sel_hi:[1,0]
	v_pk_mul_f32 v[80:81], v[2:3], v[76:77] op_sel_hi:[1,0]
	v_max_f32_e32 v77, 0, v82
	v_max_f32_e32 v74, 0, v74
	v_mul_f32_e32 v77, v77, v77
	v_max_f32_e32 v75, 0, v75
	v_max_f32_e32 v72, 0, v72
	v_mul_f32_e32 v74, v74, v74
	v_max_f32_e32 v82, 0, v83
	v_mul_f32_e32 v75, v75, v75
	v_max_f32_e32 v80, 0, v80
	v_mul_f32_e32 v83, v72, v72
	v_max_f32_e32 v72, 0, v73
	v_max_f32_e32 v73, 0, v81
	v_pk_mul_f32 v[46:47], v[46:47], v[76:77] op_sel_hi:[1,0]
	v_pk_mul_f32 v[44:45], v[44:45], v[76:77] op_sel_hi:[1,0]
	v_mul_f32_e32 v82, v82, v82
	v_mul_f32_e32 v80, v80, v80
	v_mul_f32_e32 v81, v72, v72
	v_mul_f32_e32 v84, v73, v73
	v_cvt_pk_bf16_f32 v72, v74, v75
	v_pk_mul_f32 v[54:55], v[54:55], v[76:77] op_sel_hi:[1,0]
	v_pk_mul_f32 v[52:53], v[52:53], v[76:77] op_sel_hi:[1,0]
	v_max_f32_e32 v44, 0, v44
	v_max_f32_e32 v45, 0, v45
	v_max_f32_e32 v46, 0, v46
	v_cvt_pk_bf16_f32 v73, v83, v81
	v_cvt_pk_bf16_f32 v74, v77, v82
	v_cvt_pk_bf16_f32 v75, v80, v84
	global_store_dwordx4 v[78:79], v[72:75], off sc1 nt
	s_nop 1
	v_max_f32_e32 v52, 0, v52
	v_mul_f32_e32 v72, v44, v44
	v_max_f32_e32 v44, 0, v53
	v_mul_f32_e32 v53, v45, v45
	v_max_f32_e32 v45, 0, v54
	v_mul_f32_e32 v54, v46, v46
	v_max_f32_e32 v46, 0, v55
	v_max_f32_e32 v47, 0, v47
	v_mul_f32_e32 v52, v52, v52
	v_mul_f32_e32 v44, v44, v44
	v_mul_f32_e32 v45, v45, v45
	v_mul_f32_e32 v46, v46, v46
	v_mul_f32_e32 v47, v47, v47
	v_cvt_pk_bf16_f32 v44, v52, v44
	v_cvt_pk_bf16_f32 v45, v45, v46
	v_cvt_pk_bf16_f32 v46, v72, v53
	v_cvt_pk_bf16_f32 v47, v54, v47
	v_lshl_add_u64 v[52:53], v[148:149], 0, s[36:37]
	global_store_dwordx4 v[52:53], v[44:47], off sc1 nt
	s_nop 1
	s_cbranch_execz .LBB0_2797
	s_andn2_b64 vcc, exec, s[6:7]
	s_mov_b64 s[0:1], -1
	s_cbranch_vccnz .LBB0_2782
	s_branch .LBB0_2800
